# chained-prefetch DMA pieces of the last K-step woven between its MFMAs (merge segment transitions, inproj item transitions)
# speedup vs baseline: 1.2642x; 1.0073x over previous
; DI void phase_inproj(const Params& p, int l, char* smem, int tid) {
;     ...
;   for (int it = blockIdx.x; it < 272 * 24; it += gridDim.x) {
;     const int mt = it / 24, nt = it % 24, m0 = mt * 128, n0 = nt * 128;
;     f32x16 acc[2][2]; zero_acc<2>(acc);
;     gemm_main<2>(p.xn + (size_t)m0 * 1024, 1024, Wt + (size_t)n0 * 1024, 1024, 1024, acc, s, tid);
.Lip_last:
	s_add_u32 s6, s12, s49
	s_cmpk_lt_u32 s6, 0x1980
	s_cbranch_scc0 .Lip_nopf
	s_mul_hi_u32 s2, s6, 0xaaaaaaab
	s_lshr_b32 s2, s2, 4
	s_mul_i32 s3, s2, 24
	s_sub_u32 s3, s6, s3
	s_lshl_b32 s2, s2, 18
	s_add_u32 s4, s96, s2
	s_addc_u32 s5, s97, 0
	s_lshl_b32 s3, s3, 18
	s_add_u32 s8, s14, s3
	s_addc_u32 s9, s15, 0
	ds_read_b128 v[82:85], v103 offset:32768
	ds_read_b128 v[90:93], v107 offset:32768
	ds_read_b128 v[86:89], v103 offset:36864
	ds_read_b128 v[94:97], v107 offset:36864
	s_waitcnt lgkmcnt(4)
	s_add_u32 m0, s10, 0x0
	v_mfma_f32_32x32x16_bf16 v[2:17], v[74:77], v[66:69], v[2:17]
	global_load_lds_dwordx4 v98, s[4:5]
	s_add_u32 m0, s10, 0x400
	v_mfma_f32_32x32x16_bf16 v[18:33], v[78:81], v[66:69], v[18:33]
	global_load_lds_dwordx4 v99, s[4:5]
	s_add_u32 m0, s10, 0x800
	v_mfma_f32_32x32x16_bf16 v[34:49], v[74:77], v[70:73], v[34:49]
	global_load_lds_dwordx4 v100, s[4:5]
	s_add_u32 m0, s10, 0xc00
	v_mfma_f32_32x32x16_bf16 v[50:65], v[78:81], v[70:73], v[50:65]
	global_load_lds_dwordx4 v101, s[4:5]
	s_add_u32 s4, s4, 128
	s_addc_u32 s5, s5, 0
	ds_read_b128 v[66:69], v104 offset:32768
	ds_read_b128 v[74:77], v108 offset:32768
	ds_read_b128 v[70:73], v104 offset:36864
	ds_read_b128 v[78:81], v108 offset:36864
	s_waitcnt lgkmcnt(4)
	s_add_u32 m0, s10, 0x4000
	v_mfma_f32_32x32x16_bf16 v[2:17], v[90:93], v[82:85], v[2:17]
	global_load_lds_dwordx4 v98, s[8:9]
	s_add_u32 m0, s10, 0x4400
	v_mfma_f32_32x32x16_bf16 v[18:33], v[94:97], v[82:85], v[18:33]
	global_load_lds_dwordx4 v99, s[8:9]
	s_add_u32 m0, s10, 0x4800
	v_mfma_f32_32x32x16_bf16 v[34:49], v[90:93], v[86:89], v[34:49]
	global_load_lds_dwordx4 v100, s[8:9]
	s_add_u32 m0, s10, 0x4c00
	v_mfma_f32_32x32x16_bf16 v[50:65], v[94:97], v[86:89], v[50:65]
	global_load_lds_dwordx4 v101, s[8:9]
	s_add_u32 s8, s8, 128
	s_addc_u32 s9, s9, 0
	ds_read_b128 v[82:85], v105 offset:32768
	ds_read_b128 v[90:93], v109 offset:32768
	ds_read_b128 v[86:89], v105 offset:36864
	ds_read_b128 v[94:97], v109 offset:36864
	s_waitcnt lgkmcnt(4)
	v_mfma_f32_32x32x16_bf16 v[2:17], v[74:77], v[66:69], v[2:17]
	v_mfma_f32_32x32x16_bf16 v[18:33], v[78:81], v[66:69], v[18:33]
	v_mfma_f32_32x32x16_bf16 v[34:49], v[74:77], v[70:73], v[34:49]
	v_mfma_f32_32x32x16_bf16 v[50:65], v[78:81], v[70:73], v[50:65]
	s_waitcnt lgkmcnt(0)
	s_barrier
	v_mfma_f32_32x32x16_bf16 v[2:17], v[90:93], v[82:85], v[2:17]
	v_mfma_f32_32x32x16_bf16 v[18:33], v[94:97], v[82:85], v[18:33]
	v_mfma_f32_32x32x16_bf16 v[34:49], v[90:93], v[86:89], v[34:49]
	v_mfma_f32_32x32x16_bf16 v[50:65], v[94:97], v[86:89], v[50:65]
	s_branch .Lip_kdone

; DI u16 f2bf(float x) { return (u16)(pack2(x, 0.f) & 0xffffu); }
; DI int crow(int i, int h) { return (i & 3) + 8 * (i >> 2) + 4 * h; }
; DI void phase_inproj(const Params& p, int l, char* smem, int tid) {
;     ...
; #pragma unroll
;     for (int mb = 0; mb < 2; mb++)
; #pragma unroll
;       for (int nb = 0; nb < 2; nb++) {
;         const int rowb = m0 + wm * 64 + mb * 32, colb = n0 + wn * 64 + nb * 32, col = colb + r;
;         if (colb < 1792) {
;           const float qs = (colb < 256) ? 0.125f * LOG2E : 1.f;
; #pragma unroll
;           for (int i = 0; i < 16; i++) p.Pk[(size_t)(rowb + crow(i, h)) * PKW + col] = f2bf(acc[mb][nb][i] * qs);
;         } else if (colb < 2592) {
; #pragma unroll
;           for (int i = 0; i < 16; i++) p.Pt[(size_t)(rowb + crow(i, h)) * PTW + col - 1792] = f2bf(acc[mb][nb][i]);
;         }
;       }
; #pragma unroll
;     for (int nb = 0; nb < 2; nb++) {
;       const int colb = n0 + wn * 64 + nb * 32;
;       if (colb >= 2592 && colb < 2976) {
.Lip_kdone:
	s_nop 7
	s_nop 7
	s_bfe_u32 s2, s10, 0x1000c
	s_lshl_b32 s2, s2, 6
	s_lshl_b32 s16, s1, 7
	s_add_u32 s16, s16, s2
	s_cmpk_lt_u32 s16, 0x700
	s_cbranch_scc1 .Lip_rows_pk
	s_cmpk_lt_u32 s16, 0x9e1
	s_cbranch_scc1 .Lip_rows_pt
	s_branch .Lip_generic

; DI unsigned pack2(float a, float b) { f32v2 v = {a, b}; return __builtin_bit_cast(unsigned, __builtin_convertvector(v, bf16v2)); }
; DI float sigm_fast(float x) { return __builtin_amdgcn_rcpf(1.f + __expf(-x)); }
; DI void phase_merge(const Params& p, int l, char* smem, int tid) {
;     ...
;         gemm_main<1>(p.xn + (size_t)m0 * 1024, 1024, p.WtM + (size_t)l * 4096 * 1024 + ((size_t)i * 1024 + n0) * 1024, 1024, 1024, m, s, tid);
; #pragma unroll
;         for (int b2 = 0; b2 < 2; b2++)
; #pragma unroll
;           for (int e = 0; e < 8; e++) sg[b2][e] = pack2(sigm_fast(m[0][b2][2 * e]), sigm_fast(m[0][b2][2 * e + 1]));
;       }
;       f32x16 t[1][2]; zero_acc<1>(t);
;       gemm_main<1>(p.G + (size_t)m0 * 1024 + i * 256, 1024, p.WtBr + ((size_t)l * 4 + i) * 1024 * 256 + (size_t)n0 * 256, 256, 256, t, s, tid);
.Lmgm_last:
	s_lshr_b32 s6, s13, 1
	s_lshl_b32 s7, s6, 9
	s_add_u32 s4, s2, 0x16720000
	s_addc_u32 s5, s3, 0
	s_add_u32 s4, s4, s7
	s_addc_u32 s5, s5, 0
	s_lshl_b32 s7, s6, 19
	s_lshr_b32 s8, s19, 2
	s_add_u32 s7, s7, s8
	s_add_u32 s8, s16, s7
	s_addc_u32 s9, s17, 0
	ds_read_b128 v[240:243], v139 offset:32768
	ds_read_b128 v[192:195], v143 offset:32768
	ds_read_b128 v[188:191], v139 offset:36864
	ds_read_b128 v[196:199], v143 offset:36864
	s_waitcnt lgkmcnt(4)
	s_add_u32 m0, s10, 0x0
	v_mfma_f32_32x32x16_bf16 v[66:81], v[232:235], v[224:227], v[66:81]
	global_load_lds_dwordx4 v200, s[4:5]
	s_add_u32 m0, s10, 0x400
	v_mfma_f32_32x32x16_bf16 v[82:97], v[236:239], v[224:227], v[82:97]
	global_load_lds_dwordx4 v201, s[4:5]
	s_add_u32 m0, s10, 0x800
	v_mfma_f32_32x32x16_bf16 v[98:113], v[232:235], v[228:231], v[98:113]
	global_load_lds_dwordx4 v202, s[4:5]
	s_add_u32 m0, s10, 0xc00
	v_mfma_f32_32x32x16_bf16 v[114:129], v[236:239], v[228:231], v[114:129]
	global_load_lds_dwordx4 v203, s[4:5]
	s_add_u32 s4, s4, 128
	s_addc_u32 s5, s5, 0
	ds_read_b128 v[224:227], v140 offset:32768
	ds_read_b128 v[232:235], v144 offset:32768
	ds_read_b128 v[228:231], v140 offset:36864
	ds_read_b128 v[236:239], v144 offset:36864
	s_waitcnt lgkmcnt(4)
	s_add_u32 m0, s10, 0x4000
	v_mfma_f32_32x32x16_bf16 v[66:81], v[192:195], v[240:243], v[66:81]
	global_load_lds_dwordx4 v130, s[8:9]
	s_add_u32 m0, s10, 0x4400
	v_mfma_f32_32x32x16_bf16 v[82:97], v[196:199], v[240:243], v[82:97]
	global_load_lds_dwordx4 v131, s[8:9]
	s_add_u32 m0, s10, 0x4800
	v_mfma_f32_32x32x16_bf16 v[98:113], v[192:195], v[188:191], v[98:113]
	global_load_lds_dwordx4 v132, s[8:9]
	s_add_u32 m0, s10, 0x4c00
	v_mfma_f32_32x32x16_bf16 v[114:129], v[196:199], v[188:191], v[114:129]
	global_load_lds_dwordx4 v133, s[8:9]
	s_add_u32 s8, s8, 128
	s_addc_u32 s9, s9, 0
	ds_read_b128 v[240:243], v141 offset:32768
	ds_read_b128 v[192:195], v145 offset:32768
	ds_read_b128 v[188:191], v141 offset:36864
	ds_read_b128 v[196:199], v145 offset:36864
	s_waitcnt lgkmcnt(4)
	v_mfma_f32_32x32x16_bf16 v[66:81], v[232:235], v[224:227], v[66:81]
	v_mfma_f32_32x32x16_bf16 v[82:97], v[236:239], v[224:227], v[82:97]
	v_mfma_f32_32x32x16_bf16 v[98:113], v[232:235], v[228:231], v[98:113]
	v_mfma_f32_32x32x16_bf16 v[114:129], v[236:239], v[228:231], v[114:129]
	s_waitcnt lgkmcnt(0)
	s_barrier
	v_mfma_f32_32x32x16_bf16 v[66:81], v[192:195], v[240:243], v[66:81]
	v_mfma_f32_32x32x16_bf16 v[82:97], v[196:199], v[240:243], v[82:97]
	v_mfma_f32_32x32x16_bf16 v[98:113], v[192:195], v[188:191], v[98:113]
	v_mfma_f32_32x32x16_bf16 v[114:129], v[196:199], v[188:191], v[114:129]
.Lmgm_kdone:
	s_nop 7
	s_nop 7
	v_mul_f32_e32 v66, 0xbfb8aa3b, v66
	v_mul_f32_e32 v67, 0xbfb8aa3b, v67
	v_mul_f32_e32 v68, 0xbfb8aa3b, v68
	v_mul_f32_e32 v69, 0xbfb8aa3b, v69
	v_mul_f32_e32 v70, 0xbfb8aa3b, v70
	v_mul_f32_e32 v71, 0xbfb8aa3b, v71
	v_mul_f32_e32 v72, 0xbfb8aa3b, v72
	v_mul_f32_e32 v73, 0xbfb8aa3b, v73
	v_exp_f32_e32 v66, v66
	v_exp_f32_e32 v67, v67
	v_exp_f32_e32 v68, v68
	v_exp_f32_e32 v69, v69
	v_exp_f32_e32 v70, v70
	v_exp_f32_e32 v71, v71
	v_exp_f32_e32 v72, v72
	v_exp_f32_e32 v73, v73
	v_add_f32_e32 v66, 1.0, v66
	v_add_f32_e32 v67, 1.0, v67
	v_add_f32_e32 v68, 1.0, v68
	v_add_f32_e32 v69, 1.0, v69
	v_add_f32_e32 v70, 1.0, v70
	v_add_f32_e32 v71, 1.0, v71
	v_add_f32_e32 v72, 1.0, v72
	v_add_f32_e32 v73, 1.0, v73
	v_rcp_f32_e32 v66, v66
	v_rcp_f32_e32 v67, v67
	v_rcp_f32_e32 v68, v68
	v_rcp_f32_e32 v69, v69
	v_rcp_f32_e32 v70, v70
	v_rcp_f32_e32 v71, v71
	v_rcp_f32_e32 v72, v72
	v_rcp_f32_e32 v73, v73
	s_nop 0
	v_cvt_pk_bf16_f32 v156, v66, v67
	v_cvt_pk_bf16_f32 v157, v68, v69
	v_cvt_pk_bf16_f32 v158, v70, v71
	v_cvt_pk_bf16_f32 v159, v72, v73
	v_mul_f32_e32 v74, 0xbfb8aa3b, v74
	v_mul_f32_e32 v75, 0xbfb8aa3b, v75
	v_mul_f32_e32 v76, 0xbfb8aa3b, v76
	v_mul_f32_e32 v77, 0xbfb8aa3b, v77
	v_mul_f32_e32 v78, 0xbfb8aa3b, v78
	v_mul_f32_e32 v79, 0xbfb8aa3b, v79
	v_mul_f32_e32 v80, 0xbfb8aa3b, v80
	v_mul_f32_e32 v81, 0xbfb8aa3b, v81
	v_exp_f32_e32 v74, v74
	v_exp_f32_e32 v75, v75
	v_exp_f32_e32 v76, v76
	v_exp_f32_e32 v77, v77
	v_exp_f32_e32 v78, v78
	v_exp_f32_e32 v79, v79
	v_exp_f32_e32 v80, v80
	v_exp_f32_e32 v81, v81
	v_add_f32_e32 v74, 1.0, v74
	v_add_f32_e32 v75, 1.0, v75
	v_add_f32_e32 v76, 1.0, v76
	v_add_f32_e32 v77, 1.0, v77
	v_add_f32_e32 v78, 1.0, v78
	v_add_f32_e32 v79, 1.0, v79
	v_add_f32_e32 v80, 1.0, v80
	v_add_f32_e32 v81, 1.0, v81
	v_rcp_f32_e32 v74, v74
	v_rcp_f32_e32 v75, v75
	v_rcp_f32_e32 v76, v76
	v_rcp_f32_e32 v77, v77
	v_rcp_f32_e32 v78, v78
	v_rcp_f32_e32 v79, v79
	v_rcp_f32_e32 v80, v80
	v_rcp_f32_e32 v81, v81
	s_nop 0
	v_cvt_pk_bf16_f32 v160, v74, v75
	v_cvt_pk_bf16_f32 v161, v76, v77
	v_cvt_pk_bf16_f32 v162, v78, v79
	v_cvt_pk_bf16_f32 v163, v80, v81
	v_mul_f32_e32 v82, 0xbfb8aa3b, v82
	v_mul_f32_e32 v83, 0xbfb8aa3b, v83
	v_mul_f32_e32 v84, 0xbfb8aa3b, v84
	v_mul_f32_e32 v85, 0xbfb8aa3b, v85
	v_mul_f32_e32 v86, 0xbfb8aa3b, v86
	v_mul_f32_e32 v87, 0xbfb8aa3b, v87
	v_mul_f32_e32 v88, 0xbfb8aa3b, v88
	v_mul_f32_e32 v89, 0xbfb8aa3b, v89
	v_exp_f32_e32 v82, v82
	v_exp_f32_e32 v83, v83
	v_exp_f32_e32 v84, v84
	v_exp_f32_e32 v85, v85
	v_exp_f32_e32 v86, v86
	v_exp_f32_e32 v87, v87
	v_exp_f32_e32 v88, v88
	v_exp_f32_e32 v89, v89
	v_add_f32_e32 v82, 1.0, v82
	v_add_f32_e32 v83, 1.0, v83
	v_add_f32_e32 v84, 1.0, v84
	v_add_f32_e32 v85, 1.0, v85
	v_add_f32_e32 v86, 1.0, v86
	v_add_f32_e32 v87, 1.0, v87
	v_add_f32_e32 v88, 1.0, v88
	v_add_f32_e32 v89, 1.0, v89
	v_rcp_f32_e32 v82, v82
	v_rcp_f32_e32 v83, v83
	v_rcp_f32_e32 v84, v84
	v_rcp_f32_e32 v85, v85
	v_rcp_f32_e32 v86, v86
	v_rcp_f32_e32 v87, v87
	v_rcp_f32_e32 v88, v88
; DI unsigned pack2(float a, float b) { f32v2 v = {a, b}; return __builtin_bit_cast(unsigned, __builtin_convertvector(v, bf16v2)); }
; DI float sigm_fast(float x) { return __builtin_amdgcn_rcpf(1.f + __expf(-x)); }
; DI void phase_merge(const Params& p, int l, char* smem, int tid) {
;     ...
;         for (int b2 = 0; b2 < 2; b2++)
; #pragma unroll
;           for (int e = 0; e < 8; e++) sg[b2][e] = pack2(sigm_fast(m[0][b2][2 * e]), sigm_fast(m[0][b2][2 * e + 1]));
	v_rcp_f32_e32 v89, v89
	s_nop 0
	v_cvt_pk_bf16_f32 v164, v82, v83
	v_cvt_pk_bf16_f32 v165, v84, v85
	v_cvt_pk_bf16_f32 v166, v86, v87
	v_cvt_pk_bf16_f32 v167, v88, v89
	v_mul_f32_e32 v90, 0xbfb8aa3b, v90
	v_mul_f32_e32 v91, 0xbfb8aa3b, v91
	v_mul_f32_e32 v92, 0xbfb8aa3b, v92
	v_mul_f32_e32 v93, 0xbfb8aa3b, v93
	v_mul_f32_e32 v94, 0xbfb8aa3b, v94
	v_mul_f32_e32 v95, 0xbfb8aa3b, v95
	v_mul_f32_e32 v96, 0xbfb8aa3b, v96
	v_mul_f32_e32 v97, 0xbfb8aa3b, v97
	v_exp_f32_e32 v90, v90
	v_exp_f32_e32 v91, v91
	v_exp_f32_e32 v92, v92
	v_exp_f32_e32 v93, v93
	v_exp_f32_e32 v94, v94
	v_exp_f32_e32 v95, v95
	v_exp_f32_e32 v96, v96
	v_exp_f32_e32 v97, v97
	v_add_f32_e32 v90, 1.0, v90
	v_add_f32_e32 v91, 1.0, v91
	v_add_f32_e32 v92, 1.0, v92
	v_add_f32_e32 v93, 1.0, v93
	v_add_f32_e32 v94, 1.0, v94
	v_add_f32_e32 v95, 1.0, v95
	v_add_f32_e32 v96, 1.0, v96
	v_add_f32_e32 v97, 1.0, v97
	v_rcp_f32_e32 v90, v90
	v_rcp_f32_e32 v91, v91
	v_rcp_f32_e32 v92, v92
	v_rcp_f32_e32 v93, v93
	v_rcp_f32_e32 v94, v94
	v_rcp_f32_e32 v95, v95
	v_rcp_f32_e32 v96, v96
	v_rcp_f32_e32 v97, v97
	s_nop 0
	v_cvt_pk_bf16_f32 v168, v90, v91
	v_cvt_pk_bf16_f32 v169, v92, v93
	v_cvt_pk_bf16_f32 v170, v94, v95
	v_cvt_pk_bf16_f32 v171, v96, v97
	v_mul_f32_e32 v98, 0xbfb8aa3b, v98
	v_mul_f32_e32 v99, 0xbfb8aa3b, v99
	v_mul_f32_e32 v100, 0xbfb8aa3b, v100
	v_mul_f32_e32 v101, 0xbfb8aa3b, v101
	v_mul_f32_e32 v102, 0xbfb8aa3b, v102
	v_mul_f32_e32 v103, 0xbfb8aa3b, v103
	v_mul_f32_e32 v104, 0xbfb8aa3b, v104
	v_mul_f32_e32 v105, 0xbfb8aa3b, v105
	v_exp_f32_e32 v98, v98
	v_exp_f32_e32 v99, v99
	v_exp_f32_e32 v100, v100
	v_exp_f32_e32 v101, v101
	v_exp_f32_e32 v102, v102
	v_exp_f32_e32 v103, v103
	v_exp_f32_e32 v104, v104
	v_exp_f32_e32 v105, v105
	v_add_f32_e32 v98, 1.0, v98
	v_add_f32_e32 v99, 1.0, v99
	v_add_f32_e32 v100, 1.0, v100
	v_add_f32_e32 v101, 1.0, v101
	v_add_f32_e32 v102, 1.0, v102
	v_add_f32_e32 v103, 1.0, v103
	v_add_f32_e32 v104, 1.0, v104
	v_add_f32_e32 v105, 1.0, v105
	v_rcp_f32_e32 v98, v98
	v_rcp_f32_e32 v99, v99
	v_rcp_f32_e32 v100, v100
	v_rcp_f32_e32 v101, v101
	v_rcp_f32_e32 v102, v102
	v_rcp_f32_e32 v103, v103
	v_rcp_f32_e32 v104, v104
	v_rcp_f32_e32 v105, v105
	s_nop 0
	v_cvt_pk_bf16_f32 v172, v98, v99
	v_cvt_pk_bf16_f32 v173, v100, v101
	v_cvt_pk_bf16_f32 v174, v102, v103
	v_cvt_pk_bf16_f32 v175, v104, v105
	v_mul_f32_e32 v106, 0xbfb8aa3b, v106
	v_mul_f32_e32 v107, 0xbfb8aa3b, v107
	v_mul_f32_e32 v108, 0xbfb8aa3b, v108
	v_mul_f32_e32 v109, 0xbfb8aa3b, v109
	v_mul_f32_e32 v110, 0xbfb8aa3b, v110
	v_mul_f32_e32 v111, 0xbfb8aa3b, v111
	v_mul_f32_e32 v112, 0xbfb8aa3b, v112
	v_mul_f32_e32 v113, 0xbfb8aa3b, v113
	v_exp_f32_e32 v106, v106
	v_exp_f32_e32 v107, v107
	v_exp_f32_e32 v108, v108
	v_exp_f32_e32 v109, v109
	v_exp_f32_e32 v110, v110
	v_exp_f32_e32 v111, v111
	v_exp_f32_e32 v112, v112
	v_exp_f32_e32 v113, v113
	v_add_f32_e32 v106, 1.0, v106
	v_add_f32_e32 v107, 1.0, v107
	v_add_f32_e32 v108, 1.0, v108
	v_add_f32_e32 v109, 1.0, v109
	v_add_f32_e32 v110, 1.0, v110
	v_add_f32_e32 v111, 1.0, v111
	v_add_f32_e32 v112, 1.0, v112
	v_add_f32_e32 v113, 1.0, v113
	v_rcp_f32_e32 v106, v106
	v_rcp_f32_e32 v107, v107
	v_rcp_f32_e32 v108, v108
	v_rcp_f32_e32 v109, v109
	v_rcp_f32_e32 v110, v110
	v_rcp_f32_e32 v111, v111
	v_rcp_f32_e32 v112, v112
	v_rcp_f32_e32 v113, v113
	s_nop 0
	v_cvt_pk_bf16_f32 v176, v106, v107
	v_cvt_pk_bf16_f32 v177, v108, v109
	v_cvt_pk_bf16_f32 v178, v110, v111
	v_cvt_pk_bf16_f32 v179, v112, v113
	v_mul_f32_e32 v114, 0xbfb8aa3b, v114
	v_mul_f32_e32 v115, 0xbfb8aa3b, v115
	v_mul_f32_e32 v116, 0xbfb8aa3b, v116
	v_mul_f32_e32 v117, 0xbfb8aa3b, v117
	v_mul_f32_e32 v118, 0xbfb8aa3b, v118
	v_mul_f32_e32 v119, 0xbfb8aa3b, v119
	v_mul_f32_e32 v120, 0xbfb8aa3b, v120
	v_mul_f32_e32 v121, 0xbfb8aa3b, v121
	v_exp_f32_e32 v114, v114
	v_exp_f32_e32 v115, v115
	v_exp_f32_e32 v116, v116
	v_exp_f32_e32 v117, v117
; DI unsigned pack2(float a, float b) { f32v2 v = {a, b}; return __builtin_bit_cast(unsigned, __builtin_convertvector(v, bf16v2)); }
; DI float sigm_fast(float x) { return __builtin_amdgcn_rcpf(1.f + __expf(-x)); }
; DI void phase_merge(const Params& p, int l, char* smem, int tid) {
;     ...
;           for (int e = 0; e < 8; e++) sg[b2][e] = pack2(sigm_fast(m[0][b2][2 * e]), sigm_fast(m[0][b2][2 * e + 1]));
;       }
;       f32x16 t[1][2]; zero_acc<1>(t);
;       gemm_main<1>(p.G + (size_t)m0 * 1024 + i * 256, 1024, p.WtBr + ((size_t)l * 4 + i) * 1024 * 256 + (size_t)n0 * 256, 256, 256, t, s, tid);
	v_exp_f32_e32 v118, v118
	v_exp_f32_e32 v119, v119
	v_exp_f32_e32 v120, v120
	v_exp_f32_e32 v121, v121
	v_add_f32_e32 v114, 1.0, v114
	v_add_f32_e32 v115, 1.0, v115
	v_add_f32_e32 v116, 1.0, v116
	v_add_f32_e32 v117, 1.0, v117
	v_add_f32_e32 v118, 1.0, v118
	v_add_f32_e32 v119, 1.0, v119
	v_add_f32_e32 v120, 1.0, v120
	v_add_f32_e32 v121, 1.0, v121
	v_rcp_f32_e32 v114, v114
	v_rcp_f32_e32 v115, v115
	v_rcp_f32_e32 v116, v116
	v_rcp_f32_e32 v117, v117
	v_rcp_f32_e32 v118, v118
	v_rcp_f32_e32 v119, v119
	v_rcp_f32_e32 v120, v120
	v_rcp_f32_e32 v121, v121
	s_nop 0
	v_cvt_pk_bf16_f32 v180, v114, v115
	v_cvt_pk_bf16_f32 v181, v116, v117
	v_cvt_pk_bf16_f32 v182, v118, v119
	v_cvt_pk_bf16_f32 v183, v120, v121
	v_mul_f32_e32 v122, 0xbfb8aa3b, v122
	v_mul_f32_e32 v123, 0xbfb8aa3b, v123
	v_mul_f32_e32 v124, 0xbfb8aa3b, v124
	v_mul_f32_e32 v125, 0xbfb8aa3b, v125
	v_mul_f32_e32 v126, 0xbfb8aa3b, v126
	v_mul_f32_e32 v127, 0xbfb8aa3b, v127
	v_mul_f32_e32 v128, 0xbfb8aa3b, v128
	v_mul_f32_e32 v129, 0xbfb8aa3b, v129
	v_exp_f32_e32 v122, v122
	v_exp_f32_e32 v123, v123
	v_exp_f32_e32 v124, v124
	v_exp_f32_e32 v125, v125
	v_exp_f32_e32 v126, v126
	v_exp_f32_e32 v127, v127
	v_exp_f32_e32 v128, v128
	v_exp_f32_e32 v129, v129
	v_add_f32_e32 v122, 1.0, v122
	v_add_f32_e32 v123, 1.0, v123
	v_add_f32_e32 v124, 1.0, v124
	v_add_f32_e32 v125, 1.0, v125
	v_add_f32_e32 v126, 1.0, v126
	v_add_f32_e32 v127, 1.0, v127
	v_add_f32_e32 v128, 1.0, v128
	v_add_f32_e32 v129, 1.0, v129
	v_rcp_f32_e32 v122, v122
	v_rcp_f32_e32 v123, v123
	v_rcp_f32_e32 v124, v124
	v_rcp_f32_e32 v125, v125
	v_rcp_f32_e32 v126, v126
	v_rcp_f32_e32 v127, v127
	v_rcp_f32_e32 v128, v128
	v_rcp_f32_e32 v129, v129
	s_nop 0
	v_cvt_pk_bf16_f32 v184, v122, v123
	v_cvt_pk_bf16_f32 v185, v124, v125
	v_cvt_pk_bf16_f32 v186, v126, v127
	v_cvt_pk_bf16_f32 v187, v128, v129
	s_add_u32 s13, s13, 1
	v_mov_b32_e32 v66, 0
	v_mov_b32_e32 v67, 0
	v_mov_b32_e32 v68, 0
	v_mov_b32_e32 v69, 0
	v_mov_b32_e32 v70, 0
	v_mov_b32_e32 v71, 0
	v_mov_b32_e32 v72, 0
	v_mov_b32_e32 v73, 0
	v_mov_b32_e32 v74, 0
	v_mov_b32_e32 v75, 0
	v_mov_b32_e32 v76, 0
	v_mov_b32_e32 v77, 0
	v_mov_b32_e32 v78, 0
	v_mov_b32_e32 v79, 0
	v_mov_b32_e32 v80, 0
	v_mov_b32_e32 v81, 0
	v_mov_b32_e32 v82, 0
	v_mov_b32_e32 v83, 0
	v_mov_b32_e32 v84, 0
	v_mov_b32_e32 v85, 0
	v_mov_b32_e32 v86, 0
	v_mov_b32_e32 v87, 0
	v_mov_b32_e32 v88, 0
	v_mov_b32_e32 v89, 0
	v_mov_b32_e32 v90, 0
	v_mov_b32_e32 v91, 0
	v_mov_b32_e32 v92, 0
	v_mov_b32_e32 v93, 0
	v_mov_b32_e32 v94, 0
	v_mov_b32_e32 v95, 0
	v_mov_b32_e32 v96, 0
	v_mov_b32_e32 v97, 0
	v_mov_b32_e32 v98, 0
	v_mov_b32_e32 v99, 0
	v_mov_b32_e32 v100, 0
	v_mov_b32_e32 v101, 0
	v_mov_b32_e32 v102, 0
	v_mov_b32_e32 v103, 0
	v_mov_b32_e32 v104, 0
	v_mov_b32_e32 v105, 0
	v_mov_b32_e32 v106, 0
	v_mov_b32_e32 v107, 0
	v_mov_b32_e32 v108, 0
	v_mov_b32_e32 v109, 0
	v_mov_b32_e32 v110, 0
	v_mov_b32_e32 v111, 0
	v_mov_b32_e32 v112, 0
	v_mov_b32_e32 v113, 0
	v_mov_b32_e32 v114, 0
	v_mov_b32_e32 v115, 0
	v_mov_b32_e32 v116, 0
	v_mov_b32_e32 v117, 0
	v_mov_b32_e32 v118, 0
	v_mov_b32_e32 v119, 0
	v_mov_b32_e32 v120, 0
	v_mov_b32_e32 v121, 0
	v_mov_b32_e32 v122, 0
	v_mov_b32_e32 v123, 0
	v_mov_b32_e32 v124, 0
	v_mov_b32_e32 v125, 0
	v_mov_b32_e32 v126, 0
	v_mov_b32_e32 v127, 0
	v_mov_b32_e32 v128, 0
	v_mov_b32_e32 v129, 0
	s_waitcnt vmcnt(0) lgkmcnt(0)
	s_barrier
	ds_read_b128 v[224:227], v138 offset:0
	ds_read_b128 v[232:235], v142 offset:0
	ds_read_b128 v[228:231], v138 offset:4096
	ds_read_b128 v[236:239], v142 offset:4096
	s_add_u32 m0, s10, 0x8000
	s_nop 0
	global_load_lds_dwordx4 v200, s[4:5]
	s_add_u32 m0, s10, 0x8400
	s_nop 0
	global_load_lds_dwordx4 v201, s[4:5]
	s_add_u32 m0, s10, 0x8800
	s_nop 0
	global_load_lds_dwordx4 v202, s[4:5]
	s_add_u32 m0, s10, 0x8c00
	s_nop 0
	global_load_lds_dwordx4 v203, s[4:5]
	s_add_u32 s4, s4, 128
	s_addc_u32 s5, s5, 0
	s_mov_b32 s11, 1

; DI unsigned pack2(float a, float b) { f32v2 v = {a, b}; return __builtin_bit_cast(unsigned, __builtin_convertvector(v, bf16v2)); }
; DI float sigm_fast(float x) { return __builtin_amdgcn_rcpf(1.f + __expf(-x)); }
; DI void phase_merge(const Params& p, int l, char* smem, int tid) {
;     ...
;     for (int i = 0; i < 4; i++) {
;       if ((ZERO_MASK >> i) & 1) continue;
;       unsigned sg[2][8];
;       {
;         f32x16 m[1][2]; zero_acc<1>(m);
;         gemm_main<1>(p.xn + (size_t)m0 * 1024, 1024, p.WtM + (size_t)l * 4096 * 1024 + ((size_t)i * 1024 + n0) * 1024, 1024, 1024, m, s, tid);
; #pragma unroll
;         for (int b2 = 0; b2 < 2; b2++)
; #pragma unroll
;           for (int e = 0; e < 8; e++) sg[b2][e] = pack2(sigm_fast(m[0][b2][2 * e]), sigm_fast(m[0][b2][2 * e + 1]));
;       }
;       f32x16 t[1][2]; zero_acc<1>(t);
;       gemm_main<1>(p.G + (size_t)m0 * 1024 + i * 256, 1024, p.WtBr + ((size_t)l * 4 + i) * 1024 * 256 + (size_t)n0 * 256, 256, 256, t, s, tid);
.Lmgt_last:
	s_cmp_eq_u32 s13, 7
	s_cbranch_scc1 .Lmgt_nopf
	s_add_u32 s6, s13, 1
	s_lshr_b32 s6, s6, 1
	s_mov_b32 s4, s2
	s_mov_b32 s5, s3
	s_lshl_b32 s7, s6, 21
	s_add_u32 s7, s7, s19
	s_add_u32 s8, s14, s7
	s_addc_u32 s9, s15, 0
	ds_read_b128 v[240:243], v139 offset:32768
	ds_read_b128 v[192:195], v143 offset:32768
	ds_read_b128 v[188:191], v139 offset:36864
	ds_read_b128 v[196:199], v143 offset:36864
	s_waitcnt lgkmcnt(4)
	s_add_u32 m0, s10, 0x0
	v_mfma_f32_32x32x16_bf16 v[66:81], v[232:235], v[224:227], v[66:81]
	global_load_lds_dwordx4 v200, s[4:5]
	s_add_u32 m0, s10, 0x400
	v_mfma_f32_32x32x16_bf16 v[82:97], v[236:239], v[224:227], v[82:97]
	global_load_lds_dwordx4 v201, s[4:5]
	s_add_u32 m0, s10, 0x800
	v_mfma_f32_32x32x16_bf16 v[98:113], v[232:235], v[228:231], v[98:113]
	global_load_lds_dwordx4 v202, s[4:5]
	s_add_u32 m0, s10, 0xc00
	v_mfma_f32_32x32x16_bf16 v[114:129], v[236:239], v[228:231], v[114:129]
	global_load_lds_dwordx4 v203, s[4:5]
	s_add_u32 s4, s4, 128
	s_addc_u32 s5, s5, 0
	ds_read_b128 v[224:227], v140 offset:32768
	ds_read_b128 v[232:235], v144 offset:32768
	ds_read_b128 v[228:231], v140 offset:36864
	ds_read_b128 v[236:239], v144 offset:36864
	s_waitcnt lgkmcnt(4)
	s_add_u32 m0, s10, 0x4000
	v_mfma_f32_32x32x16_bf16 v[66:81], v[192:195], v[240:243], v[66:81]
	global_load_lds_dwordx4 v200, s[8:9]
	s_add_u32 m0, s10, 0x4400
	v_mfma_f32_32x32x16_bf16 v[82:97], v[196:199], v[240:243], v[82:97]
	global_load_lds_dwordx4 v201, s[8:9]
	s_add_u32 m0, s10, 0x4800
	v_mfma_f32_32x32x16_bf16 v[98:113], v[192:195], v[188:191], v[98:113]
	global_load_lds_dwordx4 v202, s[8:9]
	s_add_u32 m0, s10, 0x4c00
	v_mfma_f32_32x32x16_bf16 v[114:129], v[196:199], v[188:191], v[114:129]
	global_load_lds_dwordx4 v203, s[8:9]
	s_add_u32 s8, s8, 128
	s_addc_u32 s9, s9, 0
	ds_read_b128 v[240:243], v141 offset:32768
	ds_read_b128 v[192:195], v145 offset:32768
	ds_read_b128 v[188:191], v141 offset:36864
	ds_read_b128 v[196:199], v145 offset:36864
	s_waitcnt lgkmcnt(4)
	v_mfma_f32_32x32x16_bf16 v[66:81], v[232:235], v[224:227], v[66:81]
	v_mfma_f32_32x32x16_bf16 v[82:97], v[236:239], v[224:227], v[82:97]
	v_mfma_f32_32x32x16_bf16 v[98:113], v[232:235], v[228:231], v[98:113]
	v_mfma_f32_32x32x16_bf16 v[114:129], v[236:239], v[228:231], v[114:129]
	s_waitcnt lgkmcnt(0)
	s_barrier
	v_mfma_f32_32x32x16_bf16 v[66:81], v[192:195], v[240:243], v[66:81]
	v_mfma_f32_32x32x16_bf16 v[82:97], v[196:199], v[240:243], v[82:97]
	v_mfma_f32_32x32x16_bf16 v[98:113], v[192:195], v[188:191], v[98:113]
	v_mfma_f32_32x32x16_bf16 v[114:129], v[196:199], v[188:191], v[114:129]
	s_branch .Lmgt_kdone

; DI float bflo(unsigned v) { return __uint_as_float(v << 16); }
; DI float bfhi(unsigned v) { return __uint_as_float(v & 0xffff0000u); }
; DI void phase_merge(const Params& p, int l, char* smem, int tid) {
;     ...
; #pragma unroll
;       for (int b2 = 0; b2 < 2; b2++)
; #pragma unroll
;         for (int e = 0; e < 8; e++) { accT[0][b2][2 * e] += bflo(sg[b2][e]) * t[0][b2][2 * e]; accT[0][b2][2 * e + 1] += bfhi(sg[b2][e]) * t[0][b2][2 * e + 1]; }
;     }
.Lmgt_kdone:
	s_nop 7
	s_nop 7
	v_lshlrev_b32_e32 v147, 16, v156
	v_and_b32_e32 v149, 0xffff0000, v156
	v_fmac_f32_e32 v2, v147, v66
	v_fmac_f32_e32 v3, v149, v67
	v_lshlrev_b32_e32 v151, 16, v157
	v_and_b32_e32 v153, 0xffff0000, v157
	v_fmac_f32_e32 v4, v151, v68
	v_fmac_f32_e32 v5, v153, v69
	v_lshlrev_b32_e32 v147, 16, v158
	v_and_b32_e32 v149, 0xffff0000, v158
	v_fmac_f32_e32 v6, v147, v70
	v_fmac_f32_e32 v7, v149, v71
	v_lshlrev_b32_e32 v151, 16, v159
	v_and_b32_e32 v153, 0xffff0000, v159
	v_fmac_f32_e32 v8, v151, v72
	v_fmac_f32_e32 v9, v153, v73
	v_lshlrev_b32_e32 v147, 16, v160
	v_and_b32_e32 v149, 0xffff0000, v160
	v_fmac_f32_e32 v10, v147, v74
	v_fmac_f32_e32 v11, v149, v75
	v_lshlrev_b32_e32 v151, 16, v161
	v_and_b32_e32 v153, 0xffff0000, v161
	v_fmac_f32_e32 v12, v151, v76
	v_fmac_f32_e32 v13, v153, v77
	v_lshlrev_b32_e32 v147, 16, v162
	v_and_b32_e32 v149, 0xffff0000, v162
	v_fmac_f32_e32 v14, v147, v78
	v_fmac_f32_e32 v15, v149, v79
	v_lshlrev_b32_e32 v151, 16, v163
	v_and_b32_e32 v153, 0xffff0000, v163
	v_fmac_f32_e32 v16, v151, v80
	v_fmac_f32_e32 v17, v153, v81
	v_lshlrev_b32_e32 v147, 16, v164
	v_and_b32_e32 v149, 0xffff0000, v164
	v_fmac_f32_e32 v18, v147, v82
	v_fmac_f32_e32 v19, v149, v83
	v_lshlrev_b32_e32 v151, 16, v165
	v_and_b32_e32 v153, 0xffff0000, v165
	v_fmac_f32_e32 v20, v151, v84
	v_fmac_f32_e32 v21, v153, v85
	v_lshlrev_b32_e32 v147, 16, v166
	v_and_b32_e32 v149, 0xffff0000, v166
	v_fmac_f32_e32 v22, v147, v86
	v_fmac_f32_e32 v23, v149, v87
	v_lshlrev_b32_e32 v151, 16, v167
	v_and_b32_e32 v153, 0xffff0000, v167
	v_fmac_f32_e32 v24, v151, v88
	v_fmac_f32_e32 v25, v153, v89
	v_lshlrev_b32_e32 v147, 16, v168
	v_and_b32_e32 v149, 0xffff0000, v168
	v_fmac_f32_e32 v26, v147, v90
	v_fmac_f32_e32 v27, v149, v91
	v_lshlrev_b32_e32 v151, 16, v169
	v_and_b32_e32 v153, 0xffff0000, v169
	v_fmac_f32_e32 v28, v151, v92
	v_fmac_f32_e32 v29, v153, v93
	v_lshlrev_b32_e32 v147, 16, v170
	v_and_b32_e32 v149, 0xffff0000, v170
	v_fmac_f32_e32 v30, v147, v94
	v_fmac_f32_e32 v31, v149, v95
	v_lshlrev_b32_e32 v151, 16, v171
	v_and_b32_e32 v153, 0xffff0000, v171
	v_fmac_f32_e32 v32, v151, v96
	v_fmac_f32_e32 v33, v153, v97
	v_lshlrev_b32_e32 v147, 16, v172
	v_and_b32_e32 v149, 0xffff0000, v172
	v_fmac_f32_e32 v34, v147, v98
	v_fmac_f32_e32 v35, v149, v99
	v_lshlrev_b32_e32 v151, 16, v173
	v_and_b32_e32 v153, 0xffff0000, v173
	v_fmac_f32_e32 v36, v151, v100
	v_fmac_f32_e32 v37, v153, v101
	v_lshlrev_b32_e32 v147, 16, v174
	v_and_b32_e32 v149, 0xffff0000, v174
	v_fmac_f32_e32 v38, v147, v102
	v_fmac_f32_e32 v39, v149, v103
	v_lshlrev_b32_e32 v151, 16, v175
	v_and_b32_e32 v153, 0xffff0000, v175
	v_fmac_f32_e32 v40, v151, v104
	v_fmac_f32_e32 v41, v153, v105
	v_lshlrev_b32_e32 v147, 16, v176
	v_and_b32_e32 v149, 0xffff0000, v176
	v_fmac_f32_e32 v42, v147, v106
	v_fmac_f32_e32 v43, v149, v107
	v_lshlrev_b32_e32 v151, 16, v177
	v_and_b32_e32 v153, 0xffff0000, v177
	v_fmac_f32_e32 v44, v151, v108
	v_fmac_f32_e32 v45, v153, v109
	v_lshlrev_b32_e32 v147, 16, v178
	v_and_b32_e32 v149, 0xffff0000, v178
	v_fmac_f32_e32 v46, v147, v110
	v_fmac_f32_e32 v47, v149, v111
	v_lshlrev_b32_e32 v151, 16, v179
	v_and_b32_e32 v153, 0xffff0000, v179
	v_fmac_f32_e32 v48, v151, v112
	v_fmac_f32_e32 v49, v153, v113
	v_lshlrev_b32_e32 v147, 16, v180
	v_and_b32_e32 v149, 0xffff0000, v180
	v_fmac_f32_e32 v50, v147, v114
	v_fmac_f32_e32 v51, v149, v115
	v_lshlrev_b32_e32 v151, 16, v181
	v_and_b32_e32 v153, 0xffff0000, v181
	v_fmac_f32_e32 v52, v151, v116
	v_fmac_f32_e32 v53, v153, v117
	v_lshlrev_b32_e32 v147, 16, v182
	v_and_b32_e32 v149, 0xffff0000, v182
	v_fmac_f32_e32 v54, v147, v118
	v_fmac_f32_e32 v55, v149, v119
	v_lshlrev_b32_e32 v151, 16, v183
	v_and_b32_e32 v153, 0xffff0000, v183
	v_fmac_f32_e32 v56, v151, v120
	v_fmac_f32_e32 v57, v153, v121
	v_lshlrev_b32_e32 v147, 16, v184
	v_and_b32_e32 v149, 0xffff0000, v184
	v_fmac_f32_e32 v58, v147, v122
	v_fmac_f32_e32 v59, v149, v123
	v_lshlrev_b32_e32 v151, 16, v185
	v_and_b32_e32 v153, 0xffff0000, v185
	v_fmac_f32_e32 v60, v151, v124
	v_fmac_f32_e32 v61, v153, v125
	v_lshlrev_b32_e32 v147, 16, v186
	v_and_b32_e32 v149, 0xffff0000, v186
	v_fmac_f32_e32 v62, v147, v126
	v_fmac_f32_e32 v63, v149, v127
	v_lshlrev_b32_e32 v151, 16, v187
	v_and_b32_e32 v153, 0xffff0000, v187
	v_fmac_f32_e32 v64, v151, v128
	v_fmac_f32_e32 v65, v153, v129
	s_add_u32 s13, s13, 1
	s_cmp_lt_u32 s13, 8
	s_cbranch_scc1 .Lmg_seg
; DI u16 f2bf(float x) { return (u16)(pack2(x, 0.f) & 0xffffu); }
; DI int crow(int i, int h) { return (i & 3) + 8 * (i >> 2) + 4 * h; }
; DI void phase_merge(const Params& p, int l, char* smem, int tid) {
;     ...
; #pragma unroll
;     for (int nb = 0; nb < 2; nb++) {
;       const int rowb = m0 + wm * 32, col = n0 + wn * 64 + nb * 32 + r;
; #pragma unroll
;       for (int i = 0; i < 16; i++) ACC[(size_t)(rowb + crow(i, h)) * 1024 + col] = f2bf(accT[0][nb][i]);
;     }
;   }
	s_sub_u32 s6, s2, s96
	s_subb_u32 s7, s3, s97
	s_add_u32 s6, s6, s90
	s_addc_u32 s7, s7, s91
	s_lshr_b32 s8, s19, 10
	s_add_u32 s6, s6, s8
	s_addc_u32 s7, s7, 0
	v_cvt_pk_bf16_f32 v66, v2, v3
	v_cvt_pk_bf16_f32 v67, v4, v5
	ds_write_b64 v134, v[66:67] offset:0
	v_cvt_pk_bf16_f32 v68, v6, v7
	v_cvt_pk_bf16_f32 v69, v8, v9
	ds_write_b64 v134, v[68:69] offset:16
	v_cvt_pk_bf16_f32 v70, v10, v11
	v_cvt_pk_bf16_f32 v71, v12, v13
	ds_write_b64 v134, v[70:71] offset:32
	v_cvt_pk_bf16_f32 v72, v14, v15
	v_cvt_pk_bf16_f32 v73, v16, v17
	ds_write_b64 v134, v[72:73] offset:48
	v_cvt_pk_bf16_f32 v66, v18, v19
	v_cvt_pk_bf16_f32 v67, v20, v21
	ds_write_b64 v134, v[66:67] offset:64
	v_cvt_pk_bf16_f32 v68, v22, v23
	v_cvt_pk_bf16_f32 v69, v24, v25
	ds_write_b64 v134, v[68:69] offset:80
	v_cvt_pk_bf16_f32 v70, v26, v27
	v_cvt_pk_bf16_f32 v71, v28, v29
	ds_write_b64 v134, v[70:71] offset:96
	v_cvt_pk_bf16_f32 v72, v30, v31
	v_cvt_pk_bf16_f32 v73, v32, v33
	ds_write_b64 v134, v[72:73] offset:112
	v_cvt_pk_bf16_f32 v66, v34, v35
	v_cvt_pk_bf16_f32 v67, v36, v37
	ds_write_b64 v134, v[66:67] offset:4608
	v_cvt_pk_bf16_f32 v68, v38, v39
	v_cvt_pk_bf16_f32 v69, v40, v41
	ds_write_b64 v134, v[68:69] offset:4624
	v_cvt_pk_bf16_f32 v70, v42, v43
	v_cvt_pk_bf16_f32 v71, v44, v45
	ds_write_b64 v134, v[70:71] offset:4640
	v_cvt_pk_bf16_f32 v72, v46, v47
	v_cvt_pk_bf16_f32 v73, v48, v49
	ds_write_b64 v134, v[72:73] offset:4656
	v_cvt_pk_bf16_f32 v66, v50, v51
	v_cvt_pk_bf16_f32 v67, v52, v53
	ds_write_b64 v134, v[66:67] offset:4672
	v_cvt_pk_bf16_f32 v68, v54, v55
	v_cvt_pk_bf16_f32 v69, v56, v57
	ds_write_b64 v134, v[68:69] offset:4688
	v_cvt_pk_bf16_f32 v70, v58, v59
	v_cvt_pk_bf16_f32 v71, v60, v61
	ds_write_b64 v134, v[70:71] offset:4704
	v_cvt_pk_bf16_f32 v72, v62, v63
	v_cvt_pk_bf16_f32 v73, v64, v65
	ds_write_b64 v134, v[72:73] offset:4720
	ds_read_b128 v[74:77], v135 offset:0
	ds_read_b128 v[78:81], v135 offset:1152
	ds_read_b128 v[82:85], v135 offset:2304
	ds_read_b128 v[86:89], v135 offset:3456
	ds_read_b128 v[90:93], v135 offset:4608
	ds_read_b128 v[94:97], v135 offset:5760
	ds_read_b128 v[98:101], v135 offset:6912
	ds_read_b128 v[102:105], v135 offset:8064
	s_waitcnt lgkmcnt(7)
	global_store_dwordx4 v136, v[74:77], s[6:7]
	s_add_u32 s6, s6, 0x4000
	s_addc_u32 s7, s7, 0
	s_waitcnt lgkmcnt(6)
	global_store_dwordx4 v136, v[78:81], s[6:7]
	s_add_u32 s6, s6, 0x4000
	s_addc_u32 s7, s7, 0
	s_waitcnt lgkmcnt(5)
	global_store_dwordx4 v136, v[82:85], s[6:7]
	s_add_u32 s6, s6, 0x4000
	s_addc_u32 s7, s7, 0
	s_waitcnt lgkmcnt(4)
	global_store_dwordx4 v136, v[86:89], s[6:7]
	s_add_u32 s6, s6, 0x4000
	s_addc_u32 s7, s7, 0
	s_waitcnt lgkmcnt(3)
	global_store_dwordx4 v136, v[90:93], s[6:7]
	s_add_u32 s6, s6, 0x4000
	s_addc_u32 s7, s7, 0
	s_waitcnt lgkmcnt(2)
	global_store_dwordx4 v136, v[94:97], s[6:7]
	s_add_u32 s6, s6, 0x4000
	s_addc_u32 s7, s7, 0
	s_waitcnt lgkmcnt(1)
	global_store_dwordx4 v136, v[98:101], s[6:7]
	s_add_u32 s6, s6, 0x4000
	s_addc_u32 s7, s7, 0
	s_waitcnt lgkmcnt(0)
	global_store_dwordx4 v136, v[102:105], s[6:7]
	s_cmp_eq_u32 s18, 0
	s_cbranch_scc1 .Lmg_item
	s_add_u32 s12, s12, s49
	s_branch .Lmg_item
